# barrier leader path: invalidate issued with the write-back, no wait on the per-XCD generation atomic
# speedup vs baseline: 1.0036x; 1.0036x over previous
; DI unsigned xb_ld(unsigned* p)              { return __hip_atomic_load(p, __ATOMIC_RELAXED, __HIP_MEMORY_SCOPE_AGENT); }
; DI unsigned xb_add(unsigned* p, unsigned v) { return __hip_atomic_fetch_add(p, v, __ATOMIC_RELAXED, __HIP_MEMORY_SCOPE_AGENT); }
; #define XB_SPIN(cond, bar) do { unsigned _sp = 0; while (cond) { __builtin_amdgcn_s_sleep(1); \
;     if ((++_sp & 255u) == 0u) { if (xb_ld(&(bar)[XB_TMO])) break; if (_sp > XB_SPIN_CAP) { atomicAdd(&(bar)[XB_TMO], 1u); break; } } } } while (0)
; DI void xcd_barrier(const XcdBarrier& b) {
;     ...
;         const unsigned old = xb_add(&bar[XB_XSUB(b.x)], 1u);
;         const unsigned gen = old / nloc;
;         if (old + 1u == (gen + 1u) * nloc) {
;             __builtin_amdgcn_fence(__ATOMIC_RELEASE, "agent");
;             asm volatile("s_waitcnt vmcnt(0)" ::: "memory");
;             const unsigned og = xb_add(&bar[XB_TOP], 1u);
;             const unsigned tg = og / nx;
;             if (og + 1u == (tg + 1u) * nx) xb_add(&bar[XB_TOPGEN], 1u);
;             else XB_SPIN(xb_ld(&bar[XB_TOPGEN]) == tg, bar);
;             __builtin_amdgcn_fence(__ATOMIC_ACQUIRE, "agent");
;             xb_add(&bar[XB_XGEN(b.x)], 1u);
.LBB0_74:
	s_andn2_saveexec_b64 s[12:13], s[12:13]
	s_cbranch_execz .LBB0_94
	s_mov_b64 s[12:13], exec
	buffer_wbl2 sc1
	buffer_inv sc1
	s_waitcnt lgkmcnt(0)
	s_waitcnt vmcnt(0)
	v_mbcnt_lo_u32_b32 v2, s12, 0
	v_mbcnt_hi_u32_b32 v2, s13, v2
	v_cmp_eq_u32_e32 vcc, 0, v2
	s_and_saveexec_b64 s[14:15], vcc
	s_cbranch_execz .LBB0_77
	s_bcnt1_i32_b64 s12, s[12:13]
	v_mov_b32_e32 v3, 0x3000
	v_mov_b32_e32 v4, s12
	global_atomic_add v3, v3, v4, s[92:93] offset:1024 sc0

; DI unsigned xb_ld(unsigned* p)              { return __hip_atomic_load(p, __ATOMIC_RELAXED, __HIP_MEMORY_SCOPE_AGENT); }
; DI unsigned xb_add(unsigned* p, unsigned v) { return __hip_atomic_fetch_add(p, v, __ATOMIC_RELAXED, __HIP_MEMORY_SCOPE_AGENT); }
; #define XB_SPIN(cond, bar) do { unsigned _sp = 0; while (cond) { __builtin_amdgcn_s_sleep(1); \
;     if ((++_sp & 255u) == 0u) { if (xb_ld(&(bar)[XB_TMO])) break; if (_sp > XB_SPIN_CAP) { atomicAdd(&(bar)[XB_TMO], 1u); break; } } } } while (0)
; DI void xcd_barrier(const XcdBarrier& b) {
;     ...
;             const unsigned og = xb_add(&bar[XB_TOP], 1u);
;             const unsigned tg = og / nx;
;             if (og + 1u == (tg + 1u) * nx) xb_add(&bar[XB_TOPGEN], 1u);
;             else XB_SPIN(xb_ld(&bar[XB_TOPGEN]) == tg, bar);
;             __builtin_amdgcn_fence(__ATOMIC_ACQUIRE, "agent");
;             xb_add(&bar[XB_XGEN(b.x)], 1u);
;             asm volatile("s_waitcnt vmcnt(0)" ::: "memory");
.LBB0_91:
	s_or_b64 exec, exec, s[4:5]
	s_mov_b64 s[4:5], exec
	v_mbcnt_lo_u32_b32 v1, s4, 0
	v_mbcnt_hi_u32_b32 v1, s5, v1
	v_cmp_eq_u32_e32 vcc, 0, v1
	s_waitcnt vmcnt(0)
	s_and_saveexec_b64 s[10:11], vcc
	s_cbranch_execz .LBB0_93
	s_bcnt1_i32_b64 s4, s[4:5]
	v_mov_b32_e32 v1, 0x2000
	v_mov_b32_e32 v2, s4
	global_atomic_add v1, v2, s[8:9] offset:1024
.LBB0_93:
	s_or_b64 exec, exec, s[10:11]
.LBB0_94:
	s_or_b64 exec, exec, s[0:1]
	s_mov_b64 s[0:1], 0
	s_waitcnt lgkmcnt(0)
	s_barrier

; DI unsigned xb_ld(unsigned* p)              { return __hip_atomic_load(p, __ATOMIC_RELAXED, __HIP_MEMORY_SCOPE_AGENT); }
; DI unsigned xb_add(unsigned* p, unsigned v) { return __hip_atomic_fetch_add(p, v, __ATOMIC_RELAXED, __HIP_MEMORY_SCOPE_AGENT); }
; #define XB_SPIN(cond, bar) do { unsigned _sp = 0; while (cond) { __builtin_amdgcn_s_sleep(1); \
;     if ((++_sp & 255u) == 0u) { if (xb_ld(&(bar)[XB_TMO])) break; if (_sp > XB_SPIN_CAP) { atomicAdd(&(bar)[XB_TMO], 1u); break; } } } } while (0)
; DI void xcd_barrier(const XcdBarrier& b) {
;     ...
;         const unsigned old = xb_add(&bar[XB_XSUB(b.x)], 1u);
;         const unsigned gen = old / nloc;
;         if (old + 1u == (gen + 1u) * nloc) {
;             __builtin_amdgcn_fence(__ATOMIC_RELEASE, "agent");
;             asm volatile("s_waitcnt vmcnt(0)" ::: "memory");
;             const unsigned og = xb_add(&bar[XB_TOP], 1u);
;             const unsigned tg = og / nx;
;             if (og + 1u == (tg + 1u) * nx) xb_add(&bar[XB_TOPGEN], 1u);
;             else XB_SPIN(xb_ld(&bar[XB_TOPGEN]) == tg, bar);
;             __builtin_amdgcn_fence(__ATOMIC_ACQUIRE, "agent");
;             xb_add(&bar[XB_XGEN(b.x)], 1u);
.LBB0_178:
	s_andn2_saveexec_b64 s[8:9], s[40:41]
	s_cbranch_execz .LBB0_198
	s_mov_b64 s[40:41], exec
	buffer_wbl2 sc1
	buffer_inv sc1
	s_waitcnt lgkmcnt(0)
	s_waitcnt vmcnt(0)
	v_mbcnt_lo_u32_b32 v0, s40, 0
	v_mbcnt_hi_u32_b32 v0, s41, v0
	v_cmp_eq_u32_e32 vcc, 0, v0
	s_and_saveexec_b64 s[42:43], vcc
	s_cbranch_execz .LBB0_181
	s_bcnt1_i32_b64 s6, s[40:41]
	v_readlane_b32 s8, v251, 4
	v_mov_b32_e32 v3, s6
	v_readlane_b32 s9, v251, 5
	s_nop 4
	global_atomic_add v3, v1, v3, s[8:9] sc0

; DI unsigned xb_ld(unsigned* p)              { return __hip_atomic_load(p, __ATOMIC_RELAXED, __HIP_MEMORY_SCOPE_AGENT); }
; DI unsigned xb_add(unsigned* p, unsigned v) { return __hip_atomic_fetch_add(p, v, __ATOMIC_RELAXED, __HIP_MEMORY_SCOPE_AGENT); }
; #define XB_SPIN(cond, bar) do { unsigned _sp = 0; while (cond) { __builtin_amdgcn_s_sleep(1); \
;     if ((++_sp & 255u) == 0u) { if (xb_ld(&(bar)[XB_TMO])) break; if (_sp > XB_SPIN_CAP) { atomicAdd(&(bar)[XB_TMO], 1u); break; } } } } while (0)
; DI void xcd_barrier(const XcdBarrier& b) {
;     ...
;             const unsigned og = xb_add(&bar[XB_TOP], 1u);
;             const unsigned tg = og / nx;
;             if (og + 1u == (tg + 1u) * nx) xb_add(&bar[XB_TOPGEN], 1u);
;             else XB_SPIN(xb_ld(&bar[XB_TOPGEN]) == tg, bar);
;             __builtin_amdgcn_fence(__ATOMIC_ACQUIRE, "agent");
;             xb_add(&bar[XB_XGEN(b.x)], 1u);
;             asm volatile("s_waitcnt vmcnt(0)" ::: "memory");
.LBB0_195:
	s_or_b64 exec, exec, s[40:41]
	s_mov_b64 s[40:41], exec
	v_mbcnt_lo_u32_b32 v0, s40, 0
	v_mbcnt_hi_u32_b32 v0, s41, v0
	v_cmp_eq_u32_e32 vcc, 0, v0
	s_waitcnt vmcnt(0)
	s_and_saveexec_b64 s[42:43], vcc
	s_cbranch_execz .LBB0_197
	s_bcnt1_i32_b64 s6, s[40:41]
	v_readlane_b32 s8, v251, 6
	v_mov_b32_e32 v0, s6
	v_readlane_b32 s9, v251, 7
	s_nop 4
	global_atomic_add v1, v0, s[8:9]
.LBB0_197:
	s_or_b64 exec, exec, s[42:43]
.LBB0_198:
	s_or_b64 exec, exec, s[0:1]
	s_mov_b64 s[0:1], 0
	s_waitcnt lgkmcnt(0)
	s_barrier

; DI unsigned xb_ld(unsigned* p)              { return __hip_atomic_load(p, __ATOMIC_RELAXED, __HIP_MEMORY_SCOPE_AGENT); }
; DI unsigned xb_add(unsigned* p, unsigned v) { return __hip_atomic_fetch_add(p, v, __ATOMIC_RELAXED, __HIP_MEMORY_SCOPE_AGENT); }
; #define XB_SPIN(cond, bar) do { unsigned _sp = 0; while (cond) { __builtin_amdgcn_s_sleep(1); \
;     if ((++_sp & 255u) == 0u) { if (xb_ld(&(bar)[XB_TMO])) break; if (_sp > XB_SPIN_CAP) { atomicAdd(&(bar)[XB_TMO], 1u); break; } } } } while (0)
; DI void xcd_barrier(const XcdBarrier& b) {
;     ...
;         const unsigned old = xb_add(&bar[XB_XSUB(b.x)], 1u);
;         const unsigned gen = old / nloc;
;         if (old + 1u == (gen + 1u) * nloc) {
;             __builtin_amdgcn_fence(__ATOMIC_RELEASE, "agent");
;             asm volatile("s_waitcnt vmcnt(0)" ::: "memory");
;             const unsigned og = xb_add(&bar[XB_TOP], 1u);
;             const unsigned tg = og / nx;
;             if (og + 1u == (tg + 1u) * nx) xb_add(&bar[XB_TOPGEN], 1u);
;             else XB_SPIN(xb_ld(&bar[XB_TOPGEN]) == tg, bar);
;             __builtin_amdgcn_fence(__ATOMIC_ACQUIRE, "agent");
;             xb_add(&bar[XB_XGEN(b.x)], 1u);
.LBB0_349:
	s_andn2_saveexec_b64 s[12:13], s[12:13]
	s_cbranch_execz .LBB0_369
	s_mov_b64 s[12:13], exec
	buffer_wbl2 sc1
	buffer_inv sc1
	s_waitcnt lgkmcnt(0)
	s_waitcnt vmcnt(0)
	v_mbcnt_lo_u32_b32 v0, s12, 0
	v_mbcnt_hi_u32_b32 v0, s13, v0
	v_cmp_eq_u32_e32 vcc, 0, v0
	s_and_saveexec_b64 s[40:41], vcc
	s_cbranch_execz .LBB0_352
	s_bcnt1_i32_b64 s6, s[12:13]
	v_readlane_b32 s12, v251, 4
	v_mov_b32_e32 v3, s6
	v_readlane_b32 s13, v251, 5
	s_nop 4
	global_atomic_add v3, v1, v3, s[12:13] sc0

; DI unsigned xb_ld(unsigned* p)              { return __hip_atomic_load(p, __ATOMIC_RELAXED, __HIP_MEMORY_SCOPE_AGENT); }
; DI unsigned xb_add(unsigned* p, unsigned v) { return __hip_atomic_fetch_add(p, v, __ATOMIC_RELAXED, __HIP_MEMORY_SCOPE_AGENT); }
; #define XB_SPIN(cond, bar) do { unsigned _sp = 0; while (cond) { __builtin_amdgcn_s_sleep(1); \
;     if ((++_sp & 255u) == 0u) { if (xb_ld(&(bar)[XB_TMO])) break; if (_sp > XB_SPIN_CAP) { atomicAdd(&(bar)[XB_TMO], 1u); break; } } } } while (0)
; DI void xcd_barrier(const XcdBarrier& b) {
;     ...
;             const unsigned og = xb_add(&bar[XB_TOP], 1u);
;             const unsigned tg = og / nx;
;             if (og + 1u == (tg + 1u) * nx) xb_add(&bar[XB_TOPGEN], 1u);
;             else XB_SPIN(xb_ld(&bar[XB_TOPGEN]) == tg, bar);
;             __builtin_amdgcn_fence(__ATOMIC_ACQUIRE, "agent");
;             xb_add(&bar[XB_XGEN(b.x)], 1u);
;             asm volatile("s_waitcnt vmcnt(0)" ::: "memory");
.LBB0_366:
	s_or_b64 exec, exec, s[12:13]
	s_mov_b64 s[12:13], exec
	v_mbcnt_lo_u32_b32 v0, s12, 0
	v_mbcnt_hi_u32_b32 v0, s13, v0
	v_cmp_eq_u32_e32 vcc, 0, v0
	s_waitcnt vmcnt(0)
	s_and_saveexec_b64 s[40:41], vcc
	s_cbranch_execz .LBB0_368
	s_bcnt1_i32_b64 s6, s[12:13]
	v_readlane_b32 s12, v251, 6
	v_mov_b32_e32 v0, s6
	v_readlane_b32 s13, v251, 7
	s_nop 4
	global_atomic_add v1, v0, s[12:13]
.LBB0_368:
	s_or_b64 exec, exec, s[40:41]
.LBB0_369:
	s_or_b64 exec, exec, s[0:1]
	s_mov_b64 s[0:1], 0
	s_waitcnt lgkmcnt(0)
	s_barrier

; DI unsigned xb_ld(unsigned* p)              { return __hip_atomic_load(p, __ATOMIC_RELAXED, __HIP_MEMORY_SCOPE_AGENT); }
; DI unsigned xb_add(unsigned* p, unsigned v) { return __hip_atomic_fetch_add(p, v, __ATOMIC_RELAXED, __HIP_MEMORY_SCOPE_AGENT); }
; #define XB_SPIN(cond, bar) do { unsigned _sp = 0; while (cond) { __builtin_amdgcn_s_sleep(1); \
;     if ((++_sp & 255u) == 0u) { if (xb_ld(&(bar)[XB_TMO])) break; if (_sp > XB_SPIN_CAP) { atomicAdd(&(bar)[XB_TMO], 1u); break; } } } } while (0)
; DI void xcd_barrier(const XcdBarrier& b) {
;     ...
;         const unsigned old = xb_add(&bar[XB_XSUB(b.x)], 1u);
;         const unsigned gen = old / nloc;
;         if (old + 1u == (gen + 1u) * nloc) {
;             __builtin_amdgcn_fence(__ATOMIC_RELEASE, "agent");
;             asm volatile("s_waitcnt vmcnt(0)" ::: "memory");
;             const unsigned og = xb_add(&bar[XB_TOP], 1u);
;             const unsigned tg = og / nx;
;             if (og + 1u == (tg + 1u) * nx) xb_add(&bar[XB_TOPGEN], 1u);
;             else XB_SPIN(xb_ld(&bar[XB_TOPGEN]) == tg, bar);
;             __builtin_amdgcn_fence(__ATOMIC_ACQUIRE, "agent");
;             xb_add(&bar[XB_XGEN(b.x)], 1u);
.LBB0_455:
	s_andn2_saveexec_b64 s[22:23], s[40:41]
	s_cbranch_execz .LBB0_475
	s_mov_b64 s[40:41], exec
	buffer_wbl2 sc1
	buffer_inv sc1
	s_waitcnt lgkmcnt(0)
	s_waitcnt vmcnt(0)
	v_mbcnt_lo_u32_b32 v0, s40, 0
	v_mbcnt_hi_u32_b32 v0, s41, v0
	v_cmp_eq_u32_e32 vcc, 0, v0
	s_and_saveexec_b64 s[42:43], vcc
	s_cbranch_execz .LBB0_458
	s_bcnt1_i32_b64 s6, s[40:41]
	v_readlane_b32 s18, v251, 4
	v_mov_b32_e32 v3, s6
	v_readlane_b32 s19, v251, 5
	s_nop 4
	global_atomic_add v3, v1, v3, s[18:19] sc0

; DI unsigned xb_ld(unsigned* p)              { return __hip_atomic_load(p, __ATOMIC_RELAXED, __HIP_MEMORY_SCOPE_AGENT); }
; DI unsigned xb_add(unsigned* p, unsigned v) { return __hip_atomic_fetch_add(p, v, __ATOMIC_RELAXED, __HIP_MEMORY_SCOPE_AGENT); }
; #define XB_SPIN(cond, bar) do { unsigned _sp = 0; while (cond) { __builtin_amdgcn_s_sleep(1); \
;     if ((++_sp & 255u) == 0u) { if (xb_ld(&(bar)[XB_TMO])) break; if (_sp > XB_SPIN_CAP) { atomicAdd(&(bar)[XB_TMO], 1u); break; } } } } while (0)
; DI void xcd_barrier(const XcdBarrier& b) {
;     ...
;             const unsigned og = xb_add(&bar[XB_TOP], 1u);
;             const unsigned tg = og / nx;
;             if (og + 1u == (tg + 1u) * nx) xb_add(&bar[XB_TOPGEN], 1u);
;             else XB_SPIN(xb_ld(&bar[XB_TOPGEN]) == tg, bar);
;             __builtin_amdgcn_fence(__ATOMIC_ACQUIRE, "agent");
;             xb_add(&bar[XB_XGEN(b.x)], 1u);
;             asm volatile("s_waitcnt vmcnt(0)" ::: "memory");
.LBB0_472:
	s_or_b64 exec, exec, s[40:41]
	s_mov_b64 s[40:41], exec
	v_mbcnt_lo_u32_b32 v0, s40, 0
	v_mbcnt_hi_u32_b32 v0, s41, v0
	v_cmp_eq_u32_e32 vcc, 0, v0
	s_waitcnt vmcnt(0)
	s_and_saveexec_b64 s[42:43], vcc
	s_cbranch_execz .LBB0_474
	s_bcnt1_i32_b64 s6, s[40:41]
	v_readlane_b32 s18, v251, 6
	v_mov_b32_e32 v0, s6
	v_readlane_b32 s19, v251, 7
	s_nop 4
	global_atomic_add v1, v0, s[18:19]
.LBB0_474:
	s_or_b64 exec, exec, s[42:43]
.LBB0_475:
	s_or_b64 exec, exec, s[0:1]
	s_mov_b64 s[0:1], 0
	s_waitcnt lgkmcnt(0)
	s_barrier

; DI unsigned xb_add(unsigned* p, unsigned v) { return __hip_atomic_fetch_add(p, v, __ATOMIC_RELAXED, __HIP_MEMORY_SCOPE_AGENT); }
; DI void xcd_barrier(const XcdBarrier& b) {
;     ...
;             xb_add(&bar[XB_XGEN(b.x)], 1u);
;             asm volatile("s_waitcnt vmcnt(0)" ::: "memory");
.LBB0_555:
	s_or_b64 exec, exec, s[42:43]
.LBB0_556:
	s_or_b64 exec, exec, s[0:1]
	s_mov_b64 s[0:1], 0
	s_waitcnt lgkmcnt(0)
	s_barrier

; DI unsigned xb_add(unsigned* p, unsigned v) { return __hip_atomic_fetch_add(p, v, __ATOMIC_RELAXED, __HIP_MEMORY_SCOPE_AGENT); }
; DI void xcd_barrier(const XcdBarrier& b) {
;     ...
;             xb_add(&bar[XB_XGEN(b.x)], 1u);
;             asm volatile("s_waitcnt vmcnt(0)" ::: "memory");
.LBB0_677:
	s_or_b64 exec, exec, s[42:43]
.LBB0_678:
	s_or_b64 exec, exec, s[0:1]
	s_mov_b64 s[0:1], 0
	s_waitcnt lgkmcnt(0)
	s_barrier

; DI unsigned xb_add(unsigned* p, unsigned v) { return __hip_atomic_fetch_add(p, v, __ATOMIC_RELAXED, __HIP_MEMORY_SCOPE_AGENT); }
; DI void xcd_barrier(const XcdBarrier& b) {
;     ...
;             xb_add(&bar[XB_XGEN(b.x)], 1u);
;             asm volatile("s_waitcnt vmcnt(0)" ::: "memory");
.LBB0_757:
	s_or_b64 exec, exec, s[42:43]
.LBB0_758:
	s_or_b64 exec, exec, s[0:1]
	s_mov_b64 s[0:1], 0
	s_waitcnt lgkmcnt(0)
	s_barrier

; DI unsigned xb_add(unsigned* p, unsigned v) { return __hip_atomic_fetch_add(p, v, __ATOMIC_RELAXED, __HIP_MEMORY_SCOPE_AGENT); }
; DI void xcd_barrier(const XcdBarrier& b) {
;     ...
;             xb_add(&bar[XB_XGEN(b.x)], 1u);
;             asm volatile("s_waitcnt vmcnt(0)" ::: "memory");
.LBB0_904:
	s_or_b64 exec, exec, s[42:43]
.LBB0_905:
	s_or_b64 exec, exec, s[0:1]
	s_mov_b64 s[0:1], 0
	s_waitcnt lgkmcnt(0)
	s_barrier

; DI unsigned xb_ld(unsigned* p)              { return __hip_atomic_load(p, __ATOMIC_RELAXED, __HIP_MEMORY_SCOPE_AGENT); }
; DI unsigned xb_add(unsigned* p, unsigned v) { return __hip_atomic_fetch_add(p, v, __ATOMIC_RELAXED, __HIP_MEMORY_SCOPE_AGENT); }
; #define XB_SPIN(cond, bar) do { unsigned _sp = 0; while (cond) { __builtin_amdgcn_s_sleep(1); \
;     if ((++_sp & 255u) == 0u) { if (xb_ld(&(bar)[XB_TMO])) break; if (_sp > XB_SPIN_CAP) { atomicAdd(&(bar)[XB_TMO], 1u); break; } } } } while (0)
; DI void xcd_barrier(const XcdBarrier& b) {
;     ...
;         const unsigned old = xb_add(&bar[XB_XSUB(b.x)], 1u);
;         const unsigned gen = old / nloc;
;         if (old + 1u == (gen + 1u) * nloc) {
;             __builtin_amdgcn_fence(__ATOMIC_RELEASE, "agent");
;             asm volatile("s_waitcnt vmcnt(0)" ::: "memory");
;             const unsigned og = xb_add(&bar[XB_TOP], 1u);
;             const unsigned tg = og / nx;
;             if (og + 1u == (tg + 1u) * nx) xb_add(&bar[XB_TOPGEN], 1u);
;             else XB_SPIN(xb_ld(&bar[XB_TOPGEN]) == tg, bar);
;             __builtin_amdgcn_fence(__ATOMIC_ACQUIRE, "agent");
;             xb_add(&bar[XB_XGEN(b.x)], 1u);
.LBB0_956:
	s_andn2_saveexec_b64 s[2:3], s[2:3]
	s_cbranch_execz .LBB0_976
	s_mov_b64 s[2:3], exec
	buffer_wbl2 sc1
	buffer_inv sc1
	s_waitcnt lgkmcnt(0)
	s_waitcnt vmcnt(0)
	v_mbcnt_lo_u32_b32 v1, s2, 0
	v_mbcnt_hi_u32_b32 v1, s3, v1
	v_cmp_eq_u32_e32 vcc, 0, v1
	s_and_saveexec_b64 s[4:5], vcc
	s_cbranch_execz .LBB0_959
	s_bcnt1_i32_b64 s2, s[2:3]
	v_mov_b32_e32 v3, s2
	v_readlane_b32 s2, v251, 4
	v_mov_b32_e32 v2, 0
	v_readlane_b32 s3, v251, 5
	s_nop 4
	global_atomic_add v2, v2, v3, s[2:3] sc0

; DI unsigned xb_ld(unsigned* p)              { return __hip_atomic_load(p, __ATOMIC_RELAXED, __HIP_MEMORY_SCOPE_AGENT); }
; DI unsigned xb_add(unsigned* p, unsigned v) { return __hip_atomic_fetch_add(p, v, __ATOMIC_RELAXED, __HIP_MEMORY_SCOPE_AGENT); }
; #define XB_SPIN(cond, bar) do { unsigned _sp = 0; while (cond) { __builtin_amdgcn_s_sleep(1); \
;     if ((++_sp & 255u) == 0u) { if (xb_ld(&(bar)[XB_TMO])) break; if (_sp > XB_SPIN_CAP) { atomicAdd(&(bar)[XB_TMO], 1u); break; } } } } while (0)
; DI void xcd_barrier(const XcdBarrier& b) {
;     ...
;             const unsigned og = xb_add(&bar[XB_TOP], 1u);
;             const unsigned tg = og / nx;
;             if (og + 1u == (tg + 1u) * nx) xb_add(&bar[XB_TOPGEN], 1u);
;             else XB_SPIN(xb_ld(&bar[XB_TOPGEN]) == tg, bar);
;             __builtin_amdgcn_fence(__ATOMIC_ACQUIRE, "agent");
;             xb_add(&bar[XB_XGEN(b.x)], 1u);
;             asm volatile("s_waitcnt vmcnt(0)" ::: "memory");
.LBB0_973:
	s_or_b64 exec, exec, s[2:3]
	s_mov_b64 s[2:3], exec
	v_mbcnt_lo_u32_b32 v0, s2, 0
	v_mbcnt_hi_u32_b32 v0, s3, v0
	v_cmp_eq_u32_e32 vcc, 0, v0
	s_waitcnt vmcnt(0)
	s_and_saveexec_b64 s[4:5], vcc
	s_cbranch_execz .LBB0_975
	s_bcnt1_i32_b64 s2, s[2:3]
	v_mov_b32_e32 v1, s2
	v_readlane_b32 s2, v251, 6
	v_mov_b32_e32 v0, 0
	v_readlane_b32 s3, v251, 7
	s_nop 4
	global_atomic_add v0, v1, s[2:3]
.LBB0_975:
	s_or_b64 exec, exec, s[4:5]
.LBB0_976:
	s_or_b64 exec, exec, s[0:1]
	s_mov_b64 s[0:1], 0
	s_waitcnt lgkmcnt(0)
	s_barrier
